# fused RMS epilogues: row-statistic lane reductions via v_permlane16/32_swap instead of ds_bpermute
# speedup vs baseline: 1.0116x; 1.0003x over previous
.LBB0_353:
	s_add_u32 s0, s18, s6
	s_addc_u32 s1, s29, s7
	v_lshl_add_u64 v[84:85], v[202:203], 2, s[0:1]
	s_mov_b64 s[0:1], 0x1000
	v_lshl_add_u64 v[88:89], v[84:85], 0, s[0:1]
	s_movk_i32 s0, 0x1000
	v_add_co_u32_e32 v84, vcc, s0, v84
	v_mul_f32_e32 v182, v121, v121
	s_nop 0
	v_addc_co_u32_e32 v85, vcc, 0, v85, vcc
	global_load_dwordx4 v[96:99], v[84:85], off
	s_nop 0
	global_load_dwordx4 v[84:87], v[88:89], off offset:528
	global_load_dwordx4 v[92:95], v[88:89], off offset:16
	s_nop 0
	global_load_dwordx4 v[88:91], v[88:89], off offset:512
	v_mul_f32_e32 v183, v123, v123
	v_fmac_f32_e32 v182, v120, v120
	v_fmac_f32_e32 v183, v122, v122
	v_add_f32_e32 v182, v182, v183
	v_mul_f32_e32 v183, v129, v129
	v_mul_f32_e32 v184, v131, v131
	v_fmac_f32_e32 v183, v128, v128
	v_fmac_f32_e32 v184, v130, v130
	v_add_f32_e32 v183, v183, v184
	v_add_f32_e32 v182, v182, v183
	v_mul_f32_e32 v183, v117, v117
	v_mul_f32_e32 v184, v119, v119
	v_fmac_f32_e32 v183, v116, v116
	v_fmac_f32_e32 v184, v118, v118
	v_and_b32_e32 v181, 64, v226
	v_add_f32_e32 v183, v183, v184
	v_xor_b32_e32 v1, 16, v226
	v_add_u32_e32 v181, 64, v181
	v_add_f32_e32 v182, v182, v183
	v_mul_f32_e32 v183, v125, v125
	v_mul_f32_e32 v184, v127, v127
	v_cmp_lt_i32_e32 vcc, v1, v181
	v_fmac_f32_e32 v183, v124, v124
	v_fmac_f32_e32 v184, v126, v126
	v_cndmask_b32_e32 v1, v226, v1, vcc
	v_add_f32_e32 v183, v183, v184
	v_lshlrev_b32_e32 v1, 2, v1
	v_add_f32_e32 v182, v182, v183
	v_mov_b32_e32 v183, v182
	s_nop 1
	v_permlane16_swap_b32_e32 v183, v182
	v_xor_b32_e32 v184, 32, v226
	v_cmp_lt_i32_e32 vcc, v184, v181
	v_and_b32_e32 v217, 63, v180
	s_lshl_b32 s0, s5, 2
	v_cndmask_b32_e32 v181, v226, v184, vcc
	v_lshlrev_b32_e32 v228, 2, v181
	s_waitcnt lgkmcnt(0)
	v_add_f32_e32 v181, v182, v183
	v_mov_b32_e32 v182, v181
	s_nop 1
	v_permlane32_swap_b32_e32 v182, v181
	v_cmp_gt_u32_e64 s[38:39], 16, v217
	s_add_i32 s10, s0, 0
	s_and_saveexec_b64 s[0:1], s[38:39]
	s_cbranch_execz .LBB0_355
	s_lshl_b32 s5, s21, 10
	s_add_i32 s5, s10, s5
	v_lshl_add_u32 v183, v193, 4, s5
	s_waitcnt lgkmcnt(0)
	v_add_f32_e32 v181, v181, v182
	ds_write_b32 v183, v181
.LBB0_355:
	s_or_b64 exec, exec, s[0:1]
	v_mul_f32_e32 v181, v141, v141
	s_waitcnt lgkmcnt(0)
	v_mul_f32_e32 v182, v143, v143
	v_fmac_f32_e32 v181, v140, v140
	v_fmac_f32_e32 v182, v142, v142
	v_add_f32_e32 v181, v181, v182
	v_mul_f32_e32 v182, v145, v145
	v_mul_f32_e32 v183, v147, v147
	v_fmac_f32_e32 v182, v144, v144
	v_fmac_f32_e32 v183, v146, v146
	v_add_f32_e32 v182, v182, v183
	v_add_f32_e32 v181, v181, v182
	v_mul_f32_e32 v182, v137, v137
	v_mul_f32_e32 v183, v139, v139
	v_fmac_f32_e32 v182, v136, v136
	v_fmac_f32_e32 v183, v138, v138
	v_add_f32_e32 v182, v182, v183
	v_add_f32_e32 v181, v181, v182
	v_mul_f32_e32 v182, v133, v133
	v_mul_f32_e32 v183, v135, v135
	v_fmac_f32_e32 v182, v132, v132
	v_fmac_f32_e32 v183, v134, v134
	v_add_f32_e32 v182, v182, v183
	v_add_f32_e32 v181, v181, v182
	v_mov_b32_e32 v182, v181
	s_nop 1
	v_permlane16_swap_b32_e32 v182, v181
	s_waitcnt lgkmcnt(0)
	v_add_f32_e32 v181, v181, v182
	v_mov_b32_e32 v182, v181
	s_nop 1
	v_permlane32_swap_b32_e32 v182, v181
	s_and_saveexec_b64 s[0:1], s[38:39]
	s_cbranch_execz .LBB0_357
	s_lshl_b32 s5, s21, 10
	s_add_i32 s5, s10, s5
	v_lshl_add_u32 v183, v193, 4, s5
	s_waitcnt lgkmcnt(0)
	v_add_f32_e32 v181, v181, v182
	ds_write_b32 v183, v181 offset:256
.LBB0_357:
	s_or_b64 exec, exec, s[0:1]
	v_mul_f32_e32 v181, v113, v113
	s_waitcnt lgkmcnt(0)
	v_mul_f32_e32 v182, v115, v115
	v_fmac_f32_e32 v181, v112, v112
	v_fmac_f32_e32 v182, v114, v114
	v_add_f32_e32 v181, v181, v182
	v_mul_f32_e32 v182, v109, v109
	v_mul_f32_e32 v183, v111, v111
	v_fmac_f32_e32 v182, v108, v108
	v_fmac_f32_e32 v183, v110, v110
	v_add_f32_e32 v182, v182, v183
	v_add_f32_e32 v181, v181, v182
	v_mul_f32_e32 v182, v105, v105
	v_mul_f32_e32 v183, v107, v107
	v_fmac_f32_e32 v182, v104, v104
	v_fmac_f32_e32 v183, v106, v106
	v_add_f32_e32 v182, v182, v183
	v_add_f32_e32 v181, v181, v182
	v_mul_f32_e32 v182, v101, v101
	v_mul_f32_e32 v183, v103, v103
	v_fmac_f32_e32 v182, v100, v100
	v_fmac_f32_e32 v183, v102, v102
	v_add_f32_e32 v182, v182, v183
	v_add_f32_e32 v181, v181, v182
	v_mov_b32_e32 v182, v181
	s_nop 1
	v_permlane16_swap_b32_e32 v182, v181
	s_waitcnt lgkmcnt(0)
	v_add_f32_e32 v181, v181, v182
	v_mov_b32_e32 v182, v181
	s_nop 1
	v_permlane32_swap_b32_e32 v182, v181
	s_and_saveexec_b64 s[0:1], s[38:39]
	s_cbranch_execz .LBB0_359
	s_lshl_b32 s5, s21, 10
	s_add_i32 s5, s10, s5
	v_lshl_add_u32 v183, v193, 4, s5
	s_waitcnt lgkmcnt(0)
	v_add_f32_e32 v181, v181, v182
	ds_write_b32 v183, v181 offset:512
.LBB0_359:
	s_or_b64 exec, exec, s[0:1]
	v_mul_f32_e32 v181, v81, v81
	s_waitcnt lgkmcnt(0)
	v_mul_f32_e32 v182, v83, v83
	v_fmac_f32_e32 v181, v80, v80
	v_fmac_f32_e32 v182, v82, v82
	v_add_f32_e32 v181, v181, v182
	v_mul_f32_e32 v182, v77, v77
	v_mul_f32_e32 v183, v79, v79
	v_fmac_f32_e32 v182, v76, v76
	v_fmac_f32_e32 v183, v78, v78
	v_add_f32_e32 v182, v182, v183
	v_add_f32_e32 v181, v181, v182
	v_mul_f32_e32 v182, v73, v73
	v_mul_f32_e32 v183, v75, v75
	v_fmac_f32_e32 v182, v72, v72
	v_fmac_f32_e32 v183, v74, v74
	v_add_f32_e32 v182, v182, v183
	v_add_f32_e32 v181, v181, v182
	v_mul_f32_e32 v182, v69, v69
	v_mul_f32_e32 v183, v71, v71
	v_fmac_f32_e32 v182, v68, v68
	v_fmac_f32_e32 v183, v70, v70
	v_add_f32_e32 v182, v182, v183
	v_add_f32_e32 v181, v181, v182
	v_mov_b32_e32 v182, v181
	s_nop 1
	v_permlane16_swap_b32_e32 v182, v181
	s_waitcnt lgkmcnt(0)
	v_add_f32_e32 v181, v181, v182
	v_mov_b32_e32 v182, v181
	s_nop 1
	v_permlane32_swap_b32_e32 v182, v181
	s_and_saveexec_b64 s[0:1], s[38:39]
	s_cbranch_execz .LBB0_361
	s_lshl_b32 s5, s21, 10
	s_add_i32 s5, s10, s5
	v_lshl_add_u32 v183, v193, 4, s5
	s_waitcnt lgkmcnt(0)
	v_add_f32_e32 v181, v181, v182
	ds_write_b32 v183, v181 offset:768
.LBB0_361:
	s_or_b64 exec, exec, s[0:1]
	v_mul_f32_e32 v181, v65, v65
	s_waitcnt lgkmcnt(0)
	v_mul_f32_e32 v182, v67, v67
	v_fmac_f32_e32 v181, v64, v64
	v_fmac_f32_e32 v182, v66, v66
	v_add_f32_e32 v181, v181, v182
	v_mul_f32_e32 v182, v61, v61
	v_mul_f32_e32 v183, v63, v63
	v_fmac_f32_e32 v182, v60, v60
	v_fmac_f32_e32 v183, v62, v62
	v_add_f32_e32 v182, v182, v183
	v_add_f32_e32 v181, v181, v182
	v_mul_f32_e32 v182, v57, v57
	v_mul_f32_e32 v183, v59, v59
	v_fmac_f32_e32 v182, v56, v56
	v_fmac_f32_e32 v183, v58, v58
	v_add_f32_e32 v182, v182, v183
	v_add_f32_e32 v181, v181, v182
	v_mul_f32_e32 v182, v53, v53
	v_mul_f32_e32 v183, v55, v55
	v_fmac_f32_e32 v182, v52, v52
	v_fmac_f32_e32 v183, v54, v54
	v_add_f32_e32 v182, v182, v183
	v_add_f32_e32 v181, v181, v182
	v_mov_b32_e32 v182, v181
	s_nop 1
	v_permlane16_swap_b32_e32 v182, v181
	s_waitcnt lgkmcnt(0)
	v_add_f32_e32 v181, v181, v182
	v_mov_b32_e32 v182, v181
	s_nop 1
	v_permlane32_swap_b32_e32 v182, v181
	s_and_saveexec_b64 s[0:1], s[38:39]
	s_cbranch_execz .LBB0_363
	s_lshl_b32 s5, s21, 10
	s_add_i32 s5, s10, s5
	v_lshl_add_u32 v183, v193, 4, s5
	s_waitcnt lgkmcnt(0)
	v_add_f32_e32 v181, v181, v182
	ds_write_b32 v183, v181 offset:2048
.LBB0_363:
	s_or_b64 exec, exec, s[0:1]
	v_mul_f32_e32 v181, v49, v49
	s_waitcnt lgkmcnt(0)
	v_mul_f32_e32 v182, v51, v51
	v_fmac_f32_e32 v181, v48, v48
	v_fmac_f32_e32 v182, v50, v50
	v_add_f32_e32 v181, v181, v182
	v_mul_f32_e32 v182, v45, v45
	v_mul_f32_e32 v183, v47, v47
	v_fmac_f32_e32 v182, v44, v44
	v_fmac_f32_e32 v183, v46, v46
	v_add_f32_e32 v182, v182, v183
	v_add_f32_e32 v181, v181, v182
	v_mul_f32_e32 v182, v41, v41
	v_mul_f32_e32 v183, v43, v43
	v_fmac_f32_e32 v182, v40, v40
	v_fmac_f32_e32 v183, v42, v42
	v_add_f32_e32 v182, v182, v183
	v_add_f32_e32 v181, v181, v182
	v_mul_f32_e32 v182, v37, v37
	v_mul_f32_e32 v183, v39, v39
	v_fmac_f32_e32 v182, v36, v36
	v_fmac_f32_e32 v183, v38, v38
	v_add_f32_e32 v182, v182, v183
	v_add_f32_e32 v181, v181, v182
	v_mov_b32_e32 v182, v181
	s_nop 1
	v_permlane16_swap_b32_e32 v182, v181
	s_waitcnt lgkmcnt(0)
	v_add_f32_e32 v181, v181, v182
	v_mov_b32_e32 v182, v181
	s_nop 1
	v_permlane32_swap_b32_e32 v182, v181
	s_and_saveexec_b64 s[0:1], s[38:39]
	s_cbranch_execz .LBB0_365
	s_lshl_b32 s5, s21, 10
	s_add_i32 s5, s10, s5
	v_lshl_add_u32 v183, v193, 4, s5
	s_waitcnt lgkmcnt(0)
	v_add_f32_e32 v181, v181, v182
	ds_write_b32 v183, v181 offset:2304
.LBB0_365:
	s_or_b64 exec, exec, s[0:1]
	v_mul_f32_e32 v181, v33, v33
	s_waitcnt lgkmcnt(0)
	v_mul_f32_e32 v182, v35, v35
	v_fmac_f32_e32 v181, v32, v32
	v_fmac_f32_e32 v182, v34, v34
	v_add_f32_e32 v181, v181, v182
	v_mul_f32_e32 v182, v29, v29
	v_mul_f32_e32 v183, v31, v31
	v_fmac_f32_e32 v182, v28, v28
	v_fmac_f32_e32 v183, v30, v30
	v_add_f32_e32 v182, v182, v183
	v_add_f32_e32 v181, v181, v182
	v_mul_f32_e32 v182, v25, v25
	v_mul_f32_e32 v183, v27, v27
	v_fmac_f32_e32 v182, v24, v24
	v_fmac_f32_e32 v183, v26, v26
	v_add_f32_e32 v182, v182, v183
	v_add_f32_e32 v181, v181, v182
	v_mul_f32_e32 v182, v21, v21
	v_mul_f32_e32 v183, v23, v23
	v_fmac_f32_e32 v182, v20, v20
	v_fmac_f32_e32 v183, v22, v22
	v_add_f32_e32 v182, v182, v183
	v_add_f32_e32 v181, v181, v182
	v_mov_b32_e32 v182, v181
	s_nop 1
	v_permlane16_swap_b32_e32 v182, v181
	s_waitcnt lgkmcnt(0)
	v_add_f32_e32 v181, v181, v182
	v_mov_b32_e32 v182, v181
	s_nop 1
	v_permlane32_swap_b32_e32 v182, v181
	s_and_saveexec_b64 s[0:1], s[38:39]
	s_cbranch_execz .LBB0_367
	s_lshl_b32 s5, s21, 10
	s_add_i32 s5, s10, s5
	v_lshl_add_u32 v183, v193, 4, s5
	s_waitcnt lgkmcnt(0)
	v_add_f32_e32 v181, v181, v182
	ds_write_b32 v183, v181 offset:2560
.LBB0_367:
	s_or_b64 exec, exec, s[0:1]
	v_mul_f32_e32 v181, v17, v17
	s_waitcnt lgkmcnt(0)
	v_mul_f32_e32 v182, v19, v19
	v_fmac_f32_e32 v181, v16, v16
	v_fmac_f32_e32 v182, v18, v18
	v_add_f32_e32 v181, v181, v182
	v_mul_f32_e32 v182, v13, v13
	v_mul_f32_e32 v183, v15, v15
	v_fmac_f32_e32 v182, v12, v12
	v_fmac_f32_e32 v183, v14, v14
	v_add_f32_e32 v182, v182, v183
	v_add_f32_e32 v181, v181, v182
	v_mul_f32_e32 v182, v9, v9
	v_mul_f32_e32 v183, v11, v11
	v_fmac_f32_e32 v182, v8, v8
	v_fmac_f32_e32 v183, v10, v10
	v_add_f32_e32 v182, v182, v183
	v_add_f32_e32 v181, v181, v182
	v_mul_f32_e32 v182, v5, v5
	v_mul_f32_e32 v183, v7, v7
	v_fmac_f32_e32 v182, v4, v4
	v_fmac_f32_e32 v183, v6, v6
	v_add_f32_e32 v182, v182, v183
	v_add_f32_e32 v181, v181, v182
	v_mov_b32_e32 v182, v181
	s_nop 1
	v_permlane16_swap_b32_e32 v182, v181
	s_waitcnt lgkmcnt(0)
	v_add_f32_e32 v181, v181, v182
	v_mov_b32_e32 v182, v181
	s_nop 1
	v_permlane32_swap_b32_e32 v182, v181
	s_and_saveexec_b64 s[0:1], s[38:39]
	s_cbranch_execz .LBB0_369
	s_lshl_b32 s5, s21, 10
	s_add_i32 s5, s10, s5
	v_lshl_add_u32 v183, v193, 4, s5
	s_waitcnt lgkmcnt(0)
	v_add_f32_e32 v181, v181, v182
	ds_write_b32 v183, v181 offset:2816

.LBB0_427:
	s_waitcnt lgkmcnt(0)
	v_pk_mul_f32 v[12:13], v[12:13], v[2:3] op_sel_hi:[1,0]
	v_mul_f32_e32 v0, v121, v121
	s_waitcnt vmcnt(1)
	v_pk_fma_f32 v[12:13], v[92:93], v[12:13], v[156:157]
	v_mul_f32_e32 v92, v123, v123
	v_fmac_f32_e32 v0, v120, v120
	v_fmac_f32_e32 v92, v122, v122
	v_add_f32_e32 v0, v0, v92
	v_mul_f32_e32 v92, v129, v129
	v_mul_f32_e32 v93, v131, v131
	v_fmac_f32_e32 v92, v128, v128
	v_fmac_f32_e32 v93, v130, v130
	v_add_f32_e32 v92, v92, v93
	v_add_f32_e32 v0, v0, v92
	v_mul_f32_e32 v92, v117, v117
	v_mul_f32_e32 v93, v119, v119
	v_fmac_f32_e32 v92, v116, v116
	v_fmac_f32_e32 v93, v118, v118
	v_add_f32_e32 v92, v92, v93
	v_add_f32_e32 v0, v92, v0
	v_mul_f32_e32 v92, v125, v125
	v_mul_f32_e32 v93, v127, v127
	v_fmac_f32_e32 v92, v124, v124
	v_fmac_f32_e32 v93, v126, v126
	v_add_f32_e32 v92, v92, v93
	v_add_f32_e32 v0, v92, v0
	v_mov_b32_e32 v92, v0
	s_nop 1
	v_permlane16_swap_b32_e32 v92, v0
	v_pk_mul_f32 v[8:9], v[8:9], v[2:3] op_sel_hi:[1,0]
	v_pk_mul_f32 v[18:19], v[18:19], v[2:3] op_sel_hi:[1,0]
	s_waitcnt vmcnt(0)
	v_pk_fma_f32 v[8:9], v[88:89], v[8:9], v[152:153]
	v_pk_mul_f32 v[16:17], v[16:17], v[2:3] op_sel_hi:[1,0]
	s_waitcnt lgkmcnt(0)
	v_add_f32_e32 v0, v0, v92
	v_mov_b32_e32 v88, v0
	s_nop 1
	v_permlane32_swap_b32_e32 v88, v0
	v_pk_mul_f32 v[14:15], v[14:15], v[2:3] op_sel_hi:[1,0]
	v_pk_mul_f32 v[10:11], v[10:11], v[2:3] op_sel_hi:[1,0]
	v_pk_mul_f32 v[6:7], v[6:7], v[2:3] op_sel_hi:[1,0]
	v_pk_mul_f32 v[4:5], v[4:5], v[2:3] op_sel_hi:[1,0]
	v_pk_fma_f32 v[18:19], v[98:99], v[18:19], v[162:163]
	v_pk_fma_f32 v[16:17], v[96:97], v[16:17], v[160:161]
	v_pk_fma_f32 v[14:15], v[94:95], v[14:15], v[158:159]
	v_pk_fma_f32 v[10:11], v[90:91], v[10:11], v[154:155]
	v_pk_fma_f32 v[6:7], v[86:87], v[6:7], v[150:151]
	v_pk_fma_f32 v[4:5], v[84:85], v[4:5], v[148:149]
	s_nop 0
	s_and_saveexec_b64 s[0:1], s[38:39]
	s_cbranch_execz .LBB0_429
	s_lshl_b32 s4, s21, 10
	s_add_i32 s4, s10, s4
	v_lshl_add_u32 v2, v193, 4, s4
	s_waitcnt lgkmcnt(0)
	v_add_f32_e32 v0, v0, v88
	ds_write_b32 v2, v0
.LBB0_429:
	s_or_b64 exec, exec, s[0:1]
	v_mul_f32_e32 v0, v141, v141
	v_mul_f32_e32 v2, v143, v143
	v_fmac_f32_e32 v0, v140, v140
	v_fmac_f32_e32 v2, v142, v142
	v_add_f32_e32 v0, v0, v2
	v_mul_f32_e32 v2, v145, v145
	v_mul_f32_e32 v84, v147, v147
	v_fmac_f32_e32 v2, v144, v144
	v_fmac_f32_e32 v84, v146, v146
	v_add_f32_e32 v2, v2, v84
	v_add_f32_e32 v0, v0, v2
	v_mul_f32_e32 v2, v137, v137
	v_mul_f32_e32 v84, v139, v139
	v_fmac_f32_e32 v2, v136, v136
	v_fmac_f32_e32 v84, v138, v138
	v_add_f32_e32 v2, v2, v84
	v_add_f32_e32 v0, v2, v0
	v_mul_f32_e32 v2, v133, v133
	v_mul_f32_e32 v84, v135, v135
	v_fmac_f32_e32 v2, v132, v132
	v_fmac_f32_e32 v84, v134, v134
	v_add_f32_e32 v2, v2, v84
	v_add_f32_e32 v0, v2, v0
	v_mov_b32_e32 v2, v0
	s_nop 1
	v_permlane16_swap_b32_e32 v2, v0
	s_waitcnt lgkmcnt(0)
	v_add_f32_e32 v0, v0, v2
	v_mov_b32_e32 v2, v0
	s_nop 1
	v_permlane32_swap_b32_e32 v2, v0
	s_and_saveexec_b64 s[0:1], s[38:39]
	s_cbranch_execz .LBB0_431
	s_lshl_b32 s4, s21, 10
	s_add_i32 s4, s10, s4
	v_lshl_add_u32 v84, v193, 4, s4
	s_waitcnt lgkmcnt(0)
	v_add_f32_e32 v0, v0, v2
	ds_write_b32 v84, v0 offset:256
.LBB0_431:
	s_or_b64 exec, exec, s[0:1]
	v_mul_f32_e32 v0, v113, v113
	s_waitcnt lgkmcnt(0)
	v_mul_f32_e32 v2, v115, v115
	v_fmac_f32_e32 v0, v112, v112
	v_fmac_f32_e32 v2, v114, v114
	v_add_f32_e32 v0, v0, v2
	v_mul_f32_e32 v2, v109, v109
	v_mul_f32_e32 v84, v111, v111
	v_fmac_f32_e32 v2, v108, v108
	v_fmac_f32_e32 v84, v110, v110
	v_add_f32_e32 v2, v2, v84
	v_add_f32_e32 v0, v0, v2
	v_mul_f32_e32 v2, v105, v105
	v_mul_f32_e32 v84, v107, v107
	v_fmac_f32_e32 v2, v104, v104
	v_fmac_f32_e32 v84, v106, v106
	v_add_f32_e32 v2, v2, v84
	v_add_f32_e32 v0, v2, v0
	v_mul_f32_e32 v2, v101, v101
	v_mul_f32_e32 v84, v103, v103
	v_fmac_f32_e32 v2, v100, v100
	v_fmac_f32_e32 v84, v102, v102
	v_add_f32_e32 v2, v2, v84
	v_add_f32_e32 v0, v2, v0
	v_mov_b32_e32 v2, v0
	s_nop 1
	v_permlane16_swap_b32_e32 v2, v0
	s_waitcnt lgkmcnt(0)
	v_add_f32_e32 v0, v0, v2
	v_mov_b32_e32 v2, v0
	s_nop 1
	v_permlane32_swap_b32_e32 v2, v0
	s_and_saveexec_b64 s[0:1], s[38:39]
	s_cbranch_execz .LBB0_433
	s_lshl_b32 s4, s21, 10
	s_add_i32 s4, s10, s4
	v_lshl_add_u32 v84, v193, 4, s4
	s_waitcnt lgkmcnt(0)
	v_add_f32_e32 v0, v0, v2
	ds_write_b32 v84, v0 offset:512
.LBB0_433:
	s_or_b64 exec, exec, s[0:1]
	v_mul_f32_e32 v0, v81, v81
	s_waitcnt lgkmcnt(0)
	v_mul_f32_e32 v2, v83, v83
	v_fmac_f32_e32 v0, v80, v80
	v_fmac_f32_e32 v2, v82, v82
	v_add_f32_e32 v0, v0, v2
	v_mul_f32_e32 v2, v77, v77
	v_mul_f32_e32 v84, v79, v79
	v_fmac_f32_e32 v2, v76, v76
	v_fmac_f32_e32 v84, v78, v78
	v_add_f32_e32 v2, v2, v84
	v_add_f32_e32 v0, v0, v2
	v_mul_f32_e32 v2, v73, v73
	v_mul_f32_e32 v84, v75, v75
	v_fmac_f32_e32 v2, v72, v72
	v_fmac_f32_e32 v84, v74, v74
	v_add_f32_e32 v2, v2, v84
	v_add_f32_e32 v0, v2, v0
	v_mul_f32_e32 v2, v69, v69
	v_mul_f32_e32 v84, v71, v71
	v_fmac_f32_e32 v2, v68, v68
	v_fmac_f32_e32 v84, v70, v70
	v_add_f32_e32 v2, v2, v84
	v_add_f32_e32 v0, v2, v0
	v_mov_b32_e32 v2, v0
	s_nop 1
	v_permlane16_swap_b32_e32 v2, v0
	s_waitcnt lgkmcnt(0)
	v_add_f32_e32 v0, v0, v2
	v_mov_b32_e32 v2, v0
	s_nop 1
	v_permlane32_swap_b32_e32 v2, v0
	s_and_saveexec_b64 s[0:1], s[38:39]
	s_cbranch_execz .LBB0_435
	s_lshl_b32 s4, s21, 10
	s_add_i32 s4, s10, s4
	v_lshl_add_u32 v84, v193, 4, s4
	s_waitcnt lgkmcnt(0)
	v_add_f32_e32 v0, v0, v2
	ds_write_b32 v84, v0 offset:768
.LBB0_435:
	s_or_b64 exec, exec, s[0:1]
	v_mul_f32_e32 v0, v65, v65
	s_waitcnt lgkmcnt(0)
	v_mul_f32_e32 v2, v67, v67
	v_fmac_f32_e32 v0, v64, v64
	v_fmac_f32_e32 v2, v66, v66
	v_add_f32_e32 v0, v0, v2
	v_mul_f32_e32 v2, v61, v61
	v_mul_f32_e32 v84, v63, v63
	v_fmac_f32_e32 v2, v60, v60
	v_fmac_f32_e32 v84, v62, v62
	v_add_f32_e32 v2, v2, v84
	v_add_f32_e32 v0, v0, v2
	v_mul_f32_e32 v2, v57, v57
	v_mul_f32_e32 v84, v59, v59
	v_fmac_f32_e32 v2, v56, v56
	v_fmac_f32_e32 v84, v58, v58
	v_add_f32_e32 v2, v2, v84
	v_add_f32_e32 v0, v2, v0
	v_mul_f32_e32 v2, v53, v53
	v_mul_f32_e32 v84, v55, v55
	v_fmac_f32_e32 v2, v52, v52
	v_fmac_f32_e32 v84, v54, v54
	v_add_f32_e32 v2, v2, v84
	v_add_f32_e32 v0, v2, v0
	v_mov_b32_e32 v2, v0
	s_nop 1
	v_permlane16_swap_b32_e32 v2, v0
	s_waitcnt lgkmcnt(0)
	v_add_f32_e32 v0, v0, v2
	v_mov_b32_e32 v2, v0
	s_nop 1
	v_permlane32_swap_b32_e32 v2, v0
	s_and_saveexec_b64 s[0:1], s[38:39]
	s_cbranch_execz .LBB0_437
	s_lshl_b32 s4, s21, 10
	s_add_i32 s4, s10, s4
	v_lshl_add_u32 v84, v193, 4, s4
	s_waitcnt lgkmcnt(0)
	v_add_f32_e32 v0, v0, v2
	ds_write_b32 v84, v0 offset:2048
.LBB0_437:
	s_or_b64 exec, exec, s[0:1]
	v_mul_f32_e32 v0, v49, v49
	s_waitcnt lgkmcnt(0)
	v_mul_f32_e32 v2, v51, v51
	v_fmac_f32_e32 v0, v48, v48
	v_fmac_f32_e32 v2, v50, v50
	v_add_f32_e32 v0, v0, v2
	v_mul_f32_e32 v2, v45, v45
	v_mul_f32_e32 v84, v47, v47
	v_fmac_f32_e32 v2, v44, v44
	v_fmac_f32_e32 v84, v46, v46
	v_add_f32_e32 v2, v2, v84
	v_add_f32_e32 v0, v0, v2
	v_mul_f32_e32 v2, v41, v41
	v_mul_f32_e32 v84, v43, v43
	v_fmac_f32_e32 v2, v40, v40
	v_fmac_f32_e32 v84, v42, v42
	v_add_f32_e32 v2, v2, v84
	v_add_f32_e32 v0, v2, v0
	v_mul_f32_e32 v2, v37, v37
	v_mul_f32_e32 v84, v39, v39
	v_fmac_f32_e32 v2, v36, v36
	v_fmac_f32_e32 v84, v38, v38
	v_add_f32_e32 v2, v2, v84
	v_add_f32_e32 v0, v2, v0
	v_mov_b32_e32 v2, v0
	s_nop 1
	v_permlane16_swap_b32_e32 v2, v0
	s_waitcnt lgkmcnt(0)
	v_add_f32_e32 v0, v0, v2
	v_mov_b32_e32 v2, v0
	s_nop 1
	v_permlane32_swap_b32_e32 v2, v0
	s_and_saveexec_b64 s[0:1], s[38:39]
	s_cbranch_execz .LBB0_439
	s_lshl_b32 s4, s21, 10
	s_add_i32 s4, s10, s4
	v_lshl_add_u32 v84, v193, 4, s4
	s_waitcnt lgkmcnt(0)
	v_add_f32_e32 v0, v0, v2
	ds_write_b32 v84, v0 offset:2304
.LBB0_439:
	s_or_b64 exec, exec, s[0:1]
	v_mul_f32_e32 v0, v33, v33
	s_waitcnt lgkmcnt(0)
	v_mul_f32_e32 v2, v35, v35
	v_fmac_f32_e32 v0, v32, v32
	v_fmac_f32_e32 v2, v34, v34
	v_add_f32_e32 v0, v0, v2
	v_mul_f32_e32 v2, v29, v29
	v_mul_f32_e32 v84, v31, v31
	v_fmac_f32_e32 v2, v28, v28
	v_fmac_f32_e32 v84, v30, v30
	v_add_f32_e32 v2, v2, v84
	v_add_f32_e32 v0, v0, v2
	v_mul_f32_e32 v2, v25, v25
	v_mul_f32_e32 v84, v27, v27
	v_fmac_f32_e32 v2, v24, v24
	v_fmac_f32_e32 v84, v26, v26
	v_add_f32_e32 v2, v2, v84
	v_add_f32_e32 v0, v2, v0
	v_mul_f32_e32 v2, v21, v21
	v_mul_f32_e32 v84, v23, v23
	v_fmac_f32_e32 v2, v20, v20
	v_fmac_f32_e32 v84, v22, v22
	v_add_f32_e32 v2, v2, v84
	v_add_f32_e32 v0, v2, v0
	v_mov_b32_e32 v2, v0
	s_nop 1
	v_permlane16_swap_b32_e32 v2, v0
	s_waitcnt lgkmcnt(0)
	v_add_f32_e32 v0, v0, v2
	v_mov_b32_e32 v2, v0
	s_nop 1
	v_permlane32_swap_b32_e32 v2, v0
	s_and_saveexec_b64 s[0:1], s[38:39]
	s_cbranch_execz .LBB0_441
	s_lshl_b32 s4, s21, 10
	s_add_i32 s4, s10, s4
	v_lshl_add_u32 v84, v193, 4, s4
	s_waitcnt lgkmcnt(0)
	v_add_f32_e32 v0, v0, v2
	ds_write_b32 v84, v0 offset:2560
.LBB0_441:
	s_or_b64 exec, exec, s[0:1]
	v_mul_f32_e32 v0, v17, v17
	s_waitcnt lgkmcnt(0)
	v_mul_f32_e32 v2, v19, v19
	v_fmac_f32_e32 v0, v16, v16
	v_fmac_f32_e32 v2, v18, v18
	v_add_f32_e32 v0, v0, v2
	v_mul_f32_e32 v2, v13, v13
	v_mul_f32_e32 v84, v15, v15
	v_fmac_f32_e32 v2, v12, v12
	v_fmac_f32_e32 v84, v14, v14
	v_add_f32_e32 v2, v2, v84
	v_add_f32_e32 v0, v0, v2
	v_mul_f32_e32 v2, v9, v9
	v_mul_f32_e32 v84, v11, v11
	v_fmac_f32_e32 v2, v8, v8
	v_fmac_f32_e32 v84, v10, v10
	v_add_f32_e32 v2, v2, v84
	v_add_f32_e32 v0, v2, v0
	v_mul_f32_e32 v2, v5, v5
	v_mul_f32_e32 v84, v7, v7
	v_fmac_f32_e32 v2, v4, v4
	v_fmac_f32_e32 v84, v6, v6
	v_add_f32_e32 v2, v2, v84
	v_add_f32_e32 v0, v2, v0
	v_mov_b32_e32 v1, v0
	s_nop 1
	v_permlane16_swap_b32_e32 v1, v0
	s_waitcnt lgkmcnt(0)
	v_add_f32_e32 v0, v0, v1
	v_mov_b32_e32 v1, v0
	s_nop 1
	v_permlane32_swap_b32_e32 v1, v0
	s_and_saveexec_b64 s[0:1], s[38:39]
	s_cbranch_execz .LBB0_443
	s_lshl_b32 s4, s21, 10
	s_add_i32 s10, s10, s4
	v_lshl_add_u32 v2, v193, 4, s10
	s_waitcnt lgkmcnt(0)
	v_add_f32_e32 v0, v0, v1
	ds_write_b32 v2, v0 offset:2816

.LBB0_608:
	s_add_u32 s0, s18, s6
	s_addc_u32 s1, s29, s7
	s_add_u32 s6, s46, 0x1ea00000
	s_addc_u32 s7, s47, 0
	s_lshl_b32 s8, s36, 5
	s_lshl_b32 s9, s40, 8
	v_lshrrev_b32_e32 v0, 1, v190
	s_or_b32 s8, s9, s8
	v_and_or_b32 v0, v0, 24, s8
	s_lshl_b32 s8, s25, 8
	s_or_b32 s9, s8, 0x80
	v_ashrrev_i32_e32 v1, 31, v0
	v_add_u32_e32 v188, s8, v205
	v_add_u32_e32 v130, s9, v205
	v_lshl_add_u64 v[128:129], v[0:1], 1, s[46:47]
	s_mov_b64 s[10:11], 0x3600000
	v_ashrrev_i32_e32 v189, 31, v188
	v_ashrrev_i32_e32 v131, 31, v130
	v_lshl_add_u64 v[180:181], v[128:129], 0, s[10:11]
	v_lshl_add_u64 v[128:129], v[188:189], 2, s[6:7]
	v_lshl_add_u64 v[130:131], v[130:131], 2, s[6:7]
	v_lshlrev_b64 v[132:133], 11, v[188:189]
	v_or_b32_e32 v2, 16, v205
	s_barrier
	v_lshl_add_u64 v[132:133], v[180:181], 0, v[132:133]
	global_load_dword v214, v[128:129], off
	global_load_dword v206, v[130:131], off
	global_load_dwordx4 v[176:179], v[132:133], off
	v_add_u32_e32 v186, s8, v2
	v_add_u32_e32 v130, s9, v2
	v_ashrrev_i32_e32 v187, 31, v186
	v_ashrrev_i32_e32 v131, 31, v130
	v_lshl_add_u64 v[128:129], v[186:187], 2, s[6:7]
	v_lshl_add_u64 v[130:131], v[130:131], 2, s[6:7]
	v_or_b32_e32 v2, 32, v205
	global_load_dwordx4 v[172:175], v[132:133], off offset:256
	global_load_dword v212, v[128:129], off
	global_load_dword v204, v[130:131], off
	v_lshlrev_b64 v[128:129], 11, v[186:187]
	v_add_u32_e32 v184, s8, v2
	v_add_u32_e32 v130, s9, v2
	v_lshl_add_u64 v[128:129], v[180:181], 0, v[128:129]
	v_ashrrev_i32_e32 v185, 31, v184
	v_ashrrev_i32_e32 v131, 31, v130
	v_or_b32_e32 v2, 48, v205
	global_load_dwordx4 v[168:171], v[128:129], off
	global_load_dwordx4 v[164:167], v[128:129], off offset:256
	v_lshl_add_u64 v[128:129], v[184:185], 2, s[6:7]
	v_lshl_add_u64 v[130:131], v[130:131], 2, s[6:7]
	v_lshlrev_b64 v[132:133], 11, v[184:185]
	v_add_u32_e32 v182, s8, v2
	v_lshl_add_u64 v[132:133], v[180:181], 0, v[132:133]
	global_load_dword v210, v[128:129], off
	global_load_dword v202, v[130:131], off
	global_load_dwordx4 v[160:163], v[132:133], off
	v_ashrrev_i32_e32 v183, 31, v182
	v_add_u32_e32 v130, s9, v2
	v_lshl_add_u64 v[128:129], v[182:183], 2, s[6:7]
	v_ashrrev_i32_e32 v131, 31, v130
	v_lshl_add_u64 v[130:131], v[130:131], 2, s[6:7]
	global_load_dwordx4 v[156:159], v[132:133], off offset:256
	global_load_dword v208, v[128:129], off
	global_load_dword v2, v[130:131], off
	v_lshlrev_b64 v[128:129], 11, v[182:183]
	v_lshl_add_u64 v[128:129], v[180:181], 0, v[128:129]
	global_load_dwordx4 v[152:155], v[128:129], off
	global_load_dwordx4 v[148:151], v[128:129], off offset:256
	v_lshl_add_u64 v[128:129], v[0:1], 2, s[0:1]
	s_mov_b64 s[0:1], 0x3000
	v_lshl_add_u64 v[132:133], v[128:129], 0, s[0:1]
	s_movk_i32 s0, 0x3000
	v_add_co_u32_e32 v128, vcc, s0, v128
	v_and_b32_e32 v203, 64, v226
	s_nop 0
	v_addc_co_u32_e32 v129, vcc, 0, v129, vcc
	global_load_dwordx4 v[136:139], v[128:129], off
	s_nop 0
	global_load_dwordx4 v[128:131], v[132:133], off offset:528
	global_load_dwordx4 v[140:143], v[132:133], off offset:16
	s_nop 0
	global_load_dwordx4 v[132:135], v[132:133], off offset:512
	v_xor_b32_e32 v191, 16, v226
	v_add_u32_e32 v203, 64, v203
	v_cmp_lt_i32_e32 vcc, v191, v203
	v_mul_f32_e32 v215, v147, v147
	v_fmac_f32_e32 v215, v146, v146
	v_cndmask_b32_e32 v191, v226, v191, vcc
	v_lshlrev_b32_e32 v207, 2, v191
	v_mul_f32_e32 v191, v145, v145
	v_fmac_f32_e32 v191, v144, v144
	v_add_f32_e32 v191, v191, v215
	v_mul_f32_e32 v215, v125, v125
	v_mul_f32_e32 v216, v127, v127
	v_fmac_f32_e32 v215, v124, v124
	v_fmac_f32_e32 v216, v126, v126
	v_add_f32_e32 v215, v215, v216
	v_add_f32_e32 v191, v191, v215
	v_mul_f32_e32 v215, v121, v121
	v_mul_f32_e32 v216, v123, v123
	v_fmac_f32_e32 v215, v120, v120
	v_fmac_f32_e32 v216, v122, v122
	v_add_f32_e32 v215, v215, v216
	v_add_f32_e32 v191, v191, v215
	v_mul_f32_e32 v215, v117, v117
	v_mul_f32_e32 v216, v119, v119
	v_fmac_f32_e32 v215, v116, v116
	v_fmac_f32_e32 v216, v118, v118
	v_add_f32_e32 v215, v215, v216
	v_add_f32_e32 v191, v191, v215
	v_mov_b32_e32 v216, v191
	s_nop 1
	v_permlane16_swap_b32_e32 v216, v191
	v_xor_b32_e32 v215, 32, v226
	v_cmp_lt_i32_e32 vcc, v215, v203
	s_lshl_b32 s0, s36, 2
	s_add_i32 s10, s0, 0
	v_cndmask_b32_e32 v203, v226, v215, vcc
	v_lshlrev_b32_e32 v215, 2, v203
	s_waitcnt lgkmcnt(0)
	v_add_f32_e32 v191, v191, v216
	v_mov_b32_e32 v216, v191
	s_nop 1
	v_permlane32_swap_b32_e32 v216, v191
	v_and_b32_e32 v203, 63, v190
	v_cmp_gt_u32_e64 s[38:39], 16, v203
	s_and_saveexec_b64 s[0:1], s[38:39]
	s_cbranch_execz .LBB0_610
	s_lshl_b32 s6, s20, 10
	s_add_i32 s6, s10, s6
	v_lshl_add_u32 v217, v193, 4, s6
	s_waitcnt lgkmcnt(0)
	v_add_f32_e32 v191, v191, v216
	ds_write_b32 v217, v191
.LBB0_610:
	s_or_b64 exec, exec, s[0:1]
	v_mul_f32_e32 v191, v113, v113
	s_waitcnt lgkmcnt(0)
	v_mul_f32_e32 v216, v115, v115
	v_fmac_f32_e32 v191, v112, v112
	v_fmac_f32_e32 v216, v114, v114
	v_add_f32_e32 v191, v191, v216
	v_mul_f32_e32 v216, v109, v109
	v_mul_f32_e32 v217, v111, v111
	v_fmac_f32_e32 v216, v108, v108
	v_fmac_f32_e32 v217, v110, v110
	v_add_f32_e32 v216, v216, v217
	v_add_f32_e32 v191, v191, v216
	v_mul_f32_e32 v216, v105, v105
	v_mul_f32_e32 v217, v107, v107
	v_fmac_f32_e32 v216, v104, v104
	v_fmac_f32_e32 v217, v106, v106
	v_add_f32_e32 v216, v216, v217
	v_add_f32_e32 v191, v191, v216
	v_mul_f32_e32 v216, v101, v101
	v_mul_f32_e32 v217, v103, v103
	v_fmac_f32_e32 v216, v100, v100
	v_fmac_f32_e32 v217, v102, v102
	v_add_f32_e32 v216, v216, v217
	v_add_f32_e32 v191, v191, v216
	v_mov_b32_e32 v216, v191
	s_nop 1
	v_permlane16_swap_b32_e32 v216, v191
	s_waitcnt lgkmcnt(0)
	v_add_f32_e32 v191, v191, v216
	v_mov_b32_e32 v216, v191
	s_nop 1
	v_permlane32_swap_b32_e32 v216, v191
	s_and_saveexec_b64 s[0:1], s[38:39]
	s_cbranch_execz .LBB0_612
	s_lshl_b32 s6, s20, 10
	s_add_i32 s6, s10, s6
	v_lshl_add_u32 v217, v193, 4, s6
	s_waitcnt lgkmcnt(0)
	v_add_f32_e32 v191, v191, v216
	ds_write_b32 v217, v191 offset:256
.LBB0_612:
	s_or_b64 exec, exec, s[0:1]
	v_mul_f32_e32 v191, v97, v97
	s_waitcnt lgkmcnt(0)
	v_mul_f32_e32 v216, v99, v99
	v_fmac_f32_e32 v191, v96, v96
	v_fmac_f32_e32 v216, v98, v98
	v_add_f32_e32 v191, v191, v216
	v_mul_f32_e32 v216, v93, v93
	v_mul_f32_e32 v217, v95, v95
	v_fmac_f32_e32 v216, v92, v92
	v_fmac_f32_e32 v217, v94, v94
	v_add_f32_e32 v216, v216, v217
	v_add_f32_e32 v191, v191, v216
	v_mul_f32_e32 v216, v89, v89
	v_mul_f32_e32 v217, v91, v91
	v_fmac_f32_e32 v216, v88, v88
	v_fmac_f32_e32 v217, v90, v90
	v_add_f32_e32 v216, v216, v217
	v_add_f32_e32 v191, v191, v216
	v_mul_f32_e32 v216, v85, v85
	v_mul_f32_e32 v217, v87, v87
	v_fmac_f32_e32 v216, v84, v84
	v_fmac_f32_e32 v217, v86, v86
	v_add_f32_e32 v216, v216, v217
	v_add_f32_e32 v191, v191, v216
	v_mov_b32_e32 v216, v191
	s_nop 1
	v_permlane16_swap_b32_e32 v216, v191
	s_waitcnt lgkmcnt(0)
	v_add_f32_e32 v191, v191, v216
	v_mov_b32_e32 v216, v191
	s_nop 1
	v_permlane32_swap_b32_e32 v216, v191
	s_and_saveexec_b64 s[0:1], s[38:39]
	s_cbranch_execz .LBB0_614
	s_lshl_b32 s6, s20, 10
	s_add_i32 s6, s10, s6
	v_lshl_add_u32 v217, v193, 4, s6
	s_waitcnt lgkmcnt(0)
	v_add_f32_e32 v191, v191, v216
	ds_write_b32 v217, v191 offset:512
.LBB0_614:
	s_or_b64 exec, exec, s[0:1]
	v_mul_f32_e32 v191, v81, v81
	s_waitcnt lgkmcnt(0)
	v_mul_f32_e32 v216, v83, v83
	v_fmac_f32_e32 v191, v80, v80
	v_fmac_f32_e32 v216, v82, v82
	v_add_f32_e32 v191, v191, v216
	v_mul_f32_e32 v216, v77, v77
	v_mul_f32_e32 v217, v79, v79
	v_fmac_f32_e32 v216, v76, v76
	v_fmac_f32_e32 v217, v78, v78
	v_add_f32_e32 v216, v216, v217
	v_add_f32_e32 v191, v191, v216
	v_mul_f32_e32 v216, v73, v73
	v_mul_f32_e32 v217, v75, v75
	v_fmac_f32_e32 v216, v72, v72
	v_fmac_f32_e32 v217, v74, v74
	v_add_f32_e32 v216, v216, v217
	v_add_f32_e32 v191, v191, v216
	v_mul_f32_e32 v216, v69, v69
	v_mul_f32_e32 v217, v71, v71
	v_fmac_f32_e32 v216, v68, v68
	v_fmac_f32_e32 v217, v70, v70
	v_add_f32_e32 v216, v216, v217
	v_add_f32_e32 v191, v191, v216
	v_mov_b32_e32 v216, v191
	s_nop 1
	v_permlane16_swap_b32_e32 v216, v191
	s_waitcnt lgkmcnt(0)
	v_add_f32_e32 v191, v191, v216
	v_mov_b32_e32 v216, v191
	s_nop 1
	v_permlane32_swap_b32_e32 v216, v191
	s_and_saveexec_b64 s[0:1], s[38:39]
	s_cbranch_execz .LBB0_616
	s_lshl_b32 s6, s20, 10
	s_add_i32 s6, s10, s6
	v_lshl_add_u32 v217, v193, 4, s6
	s_waitcnt lgkmcnt(0)
	v_add_f32_e32 v191, v191, v216
	ds_write_b32 v217, v191 offset:768
.LBB0_616:
	s_or_b64 exec, exec, s[0:1]
	v_mul_f32_e32 v191, v65, v65
	s_waitcnt lgkmcnt(0)
	v_mul_f32_e32 v216, v67, v67
	v_fmac_f32_e32 v191, v64, v64
	v_fmac_f32_e32 v216, v66, v66
	v_add_f32_e32 v191, v191, v216
	v_mul_f32_e32 v216, v61, v61
	v_mul_f32_e32 v217, v63, v63
	v_fmac_f32_e32 v216, v60, v60
	v_fmac_f32_e32 v217, v62, v62
	v_add_f32_e32 v216, v216, v217
	v_add_f32_e32 v191, v191, v216
	v_mul_f32_e32 v216, v57, v57
	v_mul_f32_e32 v217, v59, v59
	v_fmac_f32_e32 v216, v56, v56
	v_fmac_f32_e32 v217, v58, v58
	v_add_f32_e32 v216, v216, v217
	v_add_f32_e32 v191, v191, v216
	v_mul_f32_e32 v216, v53, v53
	v_mul_f32_e32 v217, v55, v55
	v_fmac_f32_e32 v216, v52, v52
	v_fmac_f32_e32 v217, v54, v54
	v_add_f32_e32 v216, v216, v217
	v_add_f32_e32 v191, v191, v216
	v_mov_b32_e32 v216, v191
	s_nop 1
	v_permlane16_swap_b32_e32 v216, v191
	s_waitcnt lgkmcnt(0)
	v_add_f32_e32 v191, v191, v216
	v_mov_b32_e32 v216, v191
	s_nop 1
	v_permlane32_swap_b32_e32 v216, v191
	s_and_saveexec_b64 s[0:1], s[38:39]
	s_cbranch_execz .LBB0_618
	s_lshl_b32 s6, s20, 10
	s_add_i32 s6, s10, s6
	v_lshl_add_u32 v217, v193, 4, s6
	s_waitcnt lgkmcnt(0)
	v_add_f32_e32 v191, v191, v216
	ds_write_b32 v217, v191 offset:2048
.LBB0_618:
	s_or_b64 exec, exec, s[0:1]
	v_mul_f32_e32 v191, v49, v49
	s_waitcnt lgkmcnt(0)
	v_mul_f32_e32 v216, v51, v51
	v_fmac_f32_e32 v191, v48, v48
	v_fmac_f32_e32 v216, v50, v50
	v_add_f32_e32 v191, v191, v216
	v_mul_f32_e32 v216, v45, v45
	v_mul_f32_e32 v217, v47, v47
	v_fmac_f32_e32 v216, v44, v44
	v_fmac_f32_e32 v217, v46, v46
	v_add_f32_e32 v216, v216, v217
	v_add_f32_e32 v191, v191, v216
	v_mul_f32_e32 v216, v41, v41
	v_mul_f32_e32 v217, v43, v43
	v_fmac_f32_e32 v216, v40, v40
	v_fmac_f32_e32 v217, v42, v42
	v_add_f32_e32 v216, v216, v217
	v_add_f32_e32 v191, v191, v216
	v_mul_f32_e32 v216, v37, v37
	v_mul_f32_e32 v217, v39, v39
	v_fmac_f32_e32 v216, v36, v36
	v_fmac_f32_e32 v217, v38, v38
	v_add_f32_e32 v216, v216, v217
	v_add_f32_e32 v191, v191, v216
	v_mov_b32_e32 v216, v191
	s_nop 1
	v_permlane16_swap_b32_e32 v216, v191
	s_waitcnt lgkmcnt(0)
	v_add_f32_e32 v191, v191, v216
	v_mov_b32_e32 v216, v191
	s_nop 1
	v_permlane32_swap_b32_e32 v216, v191
	s_and_saveexec_b64 s[0:1], s[38:39]
	s_cbranch_execz .LBB0_620
	s_lshl_b32 s6, s20, 10
	s_add_i32 s6, s10, s6
	v_lshl_add_u32 v217, v193, 4, s6
	s_waitcnt lgkmcnt(0)
	v_add_f32_e32 v191, v191, v216
	ds_write_b32 v217, v191 offset:2304
.LBB0_620:
	s_or_b64 exec, exec, s[0:1]
	v_mul_f32_e32 v191, v33, v33
	s_waitcnt lgkmcnt(0)
	v_mul_f32_e32 v216, v35, v35
	v_fmac_f32_e32 v191, v32, v32
	v_fmac_f32_e32 v216, v34, v34
	v_add_f32_e32 v191, v191, v216
	v_mul_f32_e32 v216, v29, v29
	v_mul_f32_e32 v217, v31, v31
	v_fmac_f32_e32 v216, v28, v28
	v_fmac_f32_e32 v217, v30, v30
	v_add_f32_e32 v216, v216, v217
	v_add_f32_e32 v191, v191, v216
	v_mul_f32_e32 v216, v25, v25
	v_mul_f32_e32 v217, v27, v27
	v_fmac_f32_e32 v216, v24, v24
	v_fmac_f32_e32 v217, v26, v26
	v_add_f32_e32 v216, v216, v217
	v_add_f32_e32 v191, v191, v216
	v_mul_f32_e32 v216, v21, v21
	v_mul_f32_e32 v217, v23, v23
	v_fmac_f32_e32 v216, v20, v20
	v_fmac_f32_e32 v217, v22, v22
	v_add_f32_e32 v216, v216, v217
	v_add_f32_e32 v191, v191, v216
	v_mov_b32_e32 v216, v191
	s_nop 1
	v_permlane16_swap_b32_e32 v216, v191
	s_waitcnt lgkmcnt(0)
	v_add_f32_e32 v191, v191, v216
	v_mov_b32_e32 v216, v191
	s_nop 1
	v_permlane32_swap_b32_e32 v216, v191
	s_and_saveexec_b64 s[0:1], s[38:39]
	s_cbranch_execz .LBB0_622
	s_lshl_b32 s6, s20, 10
	s_add_i32 s6, s10, s6
	v_lshl_add_u32 v217, v193, 4, s6
	s_waitcnt lgkmcnt(0)
	v_add_f32_e32 v191, v191, v216
	ds_write_b32 v217, v191 offset:2560
.LBB0_622:
	s_or_b64 exec, exec, s[0:1]
	v_mul_f32_e32 v191, v17, v17
	s_waitcnt lgkmcnt(0)
	v_mul_f32_e32 v216, v19, v19
	v_fmac_f32_e32 v191, v16, v16
	v_fmac_f32_e32 v216, v18, v18
	v_add_f32_e32 v191, v191, v216
	v_mul_f32_e32 v216, v13, v13
	v_mul_f32_e32 v217, v15, v15
	v_fmac_f32_e32 v216, v12, v12
	v_fmac_f32_e32 v217, v14, v14
	v_add_f32_e32 v216, v216, v217
	v_add_f32_e32 v191, v191, v216
	v_mul_f32_e32 v216, v9, v9
	v_mul_f32_e32 v217, v11, v11
	v_fmac_f32_e32 v216, v8, v8
	v_fmac_f32_e32 v217, v10, v10
	v_add_f32_e32 v216, v216, v217
	v_add_f32_e32 v191, v191, v216
	v_mul_f32_e32 v216, v5, v5
	v_mul_f32_e32 v217, v7, v7
	v_fmac_f32_e32 v216, v4, v4
	v_fmac_f32_e32 v217, v6, v6
	v_add_f32_e32 v216, v216, v217
	v_add_f32_e32 v191, v191, v216
	v_mov_b32_e32 v216, v191
	s_nop 1
	v_permlane16_swap_b32_e32 v216, v191
	s_waitcnt lgkmcnt(0)
	v_add_f32_e32 v191, v191, v216
	v_mov_b32_e32 v216, v191
	s_nop 1
	v_permlane32_swap_b32_e32 v216, v191
	s_and_saveexec_b64 s[0:1], s[38:39]
	s_cbranch_execz .LBB0_624
	s_lshl_b32 s6, s20, 10
	s_add_i32 s6, s10, s6
	v_lshl_add_u32 v217, v193, 4, s6
	s_waitcnt lgkmcnt(0)
	v_add_f32_e32 v191, v191, v216
	ds_write_b32 v217, v191 offset:2816

.LBB0_636:
	s_andn2_b64 vcc, exec, s[0:1]
	s_cbranch_vccnz .LBB0_664
	v_mul_f32_e32 v2, v145, v145
	v_mul_f32_e32 v128, v147, v147
	v_fmac_f32_e32 v2, v144, v144
	v_fmac_f32_e32 v128, v146, v146
	v_add_f32_e32 v2, v2, v128
	v_mul_f32_e32 v128, v125, v125
	v_mul_f32_e32 v129, v127, v127
	v_fmac_f32_e32 v128, v124, v124
	v_fmac_f32_e32 v129, v126, v126
	v_add_f32_e32 v128, v128, v129
	v_add_f32_e32 v2, v2, v128
	v_mul_f32_e32 v128, v121, v121
	v_mul_f32_e32 v129, v123, v123
	v_fmac_f32_e32 v128, v120, v120
	v_fmac_f32_e32 v129, v122, v122
	v_add_f32_e32 v128, v128, v129
	v_add_f32_e32 v2, v128, v2
	v_mul_f32_e32 v128, v117, v117
	v_mul_f32_e32 v129, v119, v119
	v_fmac_f32_e32 v128, v116, v116
	v_fmac_f32_e32 v129, v118, v118
	v_add_f32_e32 v128, v128, v129
	v_add_f32_e32 v2, v128, v2
	v_mov_b32_e32 v128, v2
	s_nop 1
	v_permlane16_swap_b32_e32 v128, v2
	s_waitcnt lgkmcnt(0)
	v_add_f32_e32 v2, v2, v128
	v_mov_b32_e32 v128, v2
	s_nop 1
	v_permlane32_swap_b32_e32 v128, v2
	s_and_saveexec_b64 s[0:1], s[38:39]
	s_cbranch_execz .LBB0_639
	s_lshl_b32 s6, s20, 10
	s_add_i32 s6, s10, s6
	v_lshl_add_u32 v129, v193, 4, s6
	s_waitcnt lgkmcnt(0)
	v_add_f32_e32 v2, v2, v128
	ds_write_b32 v129, v2
.LBB0_639:
	s_or_b64 exec, exec, s[0:1]
	v_mul_f32_e32 v2, v113, v113
	s_waitcnt lgkmcnt(0)
	v_mul_f32_e32 v128, v115, v115
	v_fmac_f32_e32 v2, v112, v112
	v_fmac_f32_e32 v128, v114, v114
	v_add_f32_e32 v2, v2, v128
	v_mul_f32_e32 v128, v109, v109
	v_mul_f32_e32 v129, v111, v111
	v_fmac_f32_e32 v128, v108, v108
	v_fmac_f32_e32 v129, v110, v110
	v_add_f32_e32 v128, v128, v129
	v_add_f32_e32 v2, v2, v128
	v_mul_f32_e32 v128, v105, v105
	v_mul_f32_e32 v129, v107, v107
	v_fmac_f32_e32 v128, v104, v104
	v_fmac_f32_e32 v129, v106, v106
	v_add_f32_e32 v128, v128, v129
	v_add_f32_e32 v2, v128, v2
	v_mul_f32_e32 v128, v101, v101
	v_mul_f32_e32 v129, v103, v103
	v_fmac_f32_e32 v128, v100, v100
	v_fmac_f32_e32 v129, v102, v102
	v_add_f32_e32 v128, v128, v129
	v_add_f32_e32 v2, v128, v2
	v_mov_b32_e32 v128, v2
	s_nop 1
	v_permlane16_swap_b32_e32 v128, v2
	s_waitcnt lgkmcnt(0)
	v_add_f32_e32 v2, v2, v128
	v_mov_b32_e32 v128, v2
	s_nop 1
	v_permlane32_swap_b32_e32 v128, v2
	s_and_saveexec_b64 s[0:1], s[38:39]
	s_cbranch_execz .LBB0_641
	s_lshl_b32 s6, s20, 10
	s_add_i32 s6, s10, s6
	v_lshl_add_u32 v129, v193, 4, s6
	s_waitcnt lgkmcnt(0)
	v_add_f32_e32 v2, v2, v128
	ds_write_b32 v129, v2 offset:256
.LBB0_641:
	s_or_b64 exec, exec, s[0:1]
	v_mul_f32_e32 v2, v97, v97
	s_waitcnt lgkmcnt(0)
	v_mul_f32_e32 v128, v99, v99
	v_fmac_f32_e32 v2, v96, v96
	v_fmac_f32_e32 v128, v98, v98
	v_add_f32_e32 v2, v2, v128
	v_mul_f32_e32 v128, v93, v93
	v_mul_f32_e32 v129, v95, v95
	v_fmac_f32_e32 v128, v92, v92
	v_fmac_f32_e32 v129, v94, v94
	v_add_f32_e32 v128, v128, v129
	v_add_f32_e32 v2, v2, v128
	v_mul_f32_e32 v128, v89, v89
	v_mul_f32_e32 v129, v91, v91
	v_fmac_f32_e32 v128, v88, v88
	v_fmac_f32_e32 v129, v90, v90
	v_add_f32_e32 v128, v128, v129
	v_add_f32_e32 v2, v128, v2
	v_mul_f32_e32 v128, v85, v85
	v_mul_f32_e32 v129, v87, v87
	v_fmac_f32_e32 v128, v84, v84
	v_fmac_f32_e32 v129, v86, v86
	v_add_f32_e32 v128, v128, v129
	v_add_f32_e32 v2, v128, v2
	v_mov_b32_e32 v128, v2
	s_nop 1
	v_permlane16_swap_b32_e32 v128, v2
	s_waitcnt lgkmcnt(0)
	v_add_f32_e32 v2, v2, v128
	v_mov_b32_e32 v128, v2
	s_nop 1
	v_permlane32_swap_b32_e32 v128, v2
	s_and_saveexec_b64 s[0:1], s[38:39]
	s_cbranch_execz .LBB0_643
	s_lshl_b32 s6, s20, 10
	s_add_i32 s6, s10, s6
	v_lshl_add_u32 v129, v193, 4, s6
	s_waitcnt lgkmcnt(0)
	v_add_f32_e32 v2, v2, v128
	ds_write_b32 v129, v2 offset:512
.LBB0_643:
	s_or_b64 exec, exec, s[0:1]
	v_mul_f32_e32 v2, v81, v81
	s_waitcnt lgkmcnt(0)
	v_mul_f32_e32 v128, v83, v83
	v_fmac_f32_e32 v2, v80, v80
	v_fmac_f32_e32 v128, v82, v82
	v_add_f32_e32 v2, v2, v128
	v_mul_f32_e32 v128, v77, v77
	v_mul_f32_e32 v129, v79, v79
	v_fmac_f32_e32 v128, v76, v76
	v_fmac_f32_e32 v129, v78, v78
	v_add_f32_e32 v128, v128, v129
	v_add_f32_e32 v2, v2, v128
	v_mul_f32_e32 v128, v73, v73
	v_mul_f32_e32 v129, v75, v75
	v_fmac_f32_e32 v128, v72, v72
	v_fmac_f32_e32 v129, v74, v74
	v_add_f32_e32 v128, v128, v129
	v_add_f32_e32 v2, v128, v2
	v_mul_f32_e32 v128, v69, v69
	v_mul_f32_e32 v129, v71, v71
	v_fmac_f32_e32 v128, v68, v68
	v_fmac_f32_e32 v129, v70, v70
	v_add_f32_e32 v128, v128, v129
	v_add_f32_e32 v2, v128, v2
	v_mov_b32_e32 v128, v2
	s_nop 1
	v_permlane16_swap_b32_e32 v128, v2
	s_waitcnt lgkmcnt(0)
	v_add_f32_e32 v2, v2, v128
	v_mov_b32_e32 v128, v2
	s_nop 1
	v_permlane32_swap_b32_e32 v128, v2
	s_and_saveexec_b64 s[0:1], s[38:39]
	s_cbranch_execz .LBB0_645
	s_lshl_b32 s6, s20, 10
	s_add_i32 s6, s10, s6
	v_lshl_add_u32 v129, v193, 4, s6
	s_waitcnt lgkmcnt(0)
	v_add_f32_e32 v2, v2, v128
	ds_write_b32 v129, v2 offset:768
.LBB0_645:
	s_or_b64 exec, exec, s[0:1]
	v_mul_f32_e32 v2, v65, v65
	s_waitcnt lgkmcnt(0)
	v_mul_f32_e32 v128, v67, v67
	v_fmac_f32_e32 v2, v64, v64
	v_fmac_f32_e32 v128, v66, v66
	v_add_f32_e32 v2, v2, v128
	v_mul_f32_e32 v128, v61, v61
	v_mul_f32_e32 v129, v63, v63
	v_fmac_f32_e32 v128, v60, v60
	v_fmac_f32_e32 v129, v62, v62
	v_add_f32_e32 v128, v128, v129
	v_add_f32_e32 v2, v2, v128
	v_mul_f32_e32 v128, v57, v57
	v_mul_f32_e32 v129, v59, v59
	v_fmac_f32_e32 v128, v56, v56
	v_fmac_f32_e32 v129, v58, v58
	v_add_f32_e32 v128, v128, v129
	v_add_f32_e32 v2, v128, v2
	v_mul_f32_e32 v128, v53, v53
	v_mul_f32_e32 v129, v55, v55
	v_fmac_f32_e32 v128, v52, v52
	v_fmac_f32_e32 v129, v54, v54
	v_add_f32_e32 v128, v128, v129
	v_add_f32_e32 v2, v128, v2
	v_mov_b32_e32 v128, v2
	s_nop 1
	v_permlane16_swap_b32_e32 v128, v2
	s_waitcnt lgkmcnt(0)
	v_add_f32_e32 v2, v2, v128
	v_mov_b32_e32 v128, v2
	s_nop 1
	v_permlane32_swap_b32_e32 v128, v2
	s_and_saveexec_b64 s[0:1], s[38:39]
	s_cbranch_execz .LBB0_647
	s_lshl_b32 s6, s20, 10
	s_add_i32 s6, s10, s6
	v_lshl_add_u32 v129, v193, 4, s6
	s_waitcnt lgkmcnt(0)
	v_add_f32_e32 v2, v2, v128
	ds_write_b32 v129, v2 offset:2048
.LBB0_647:
	s_or_b64 exec, exec, s[0:1]
	v_mul_f32_e32 v2, v49, v49
	s_waitcnt lgkmcnt(0)
	v_mul_f32_e32 v128, v51, v51
	v_fmac_f32_e32 v2, v48, v48
	v_fmac_f32_e32 v128, v50, v50
	v_add_f32_e32 v2, v2, v128
	v_mul_f32_e32 v128, v45, v45
	v_mul_f32_e32 v129, v47, v47
	v_fmac_f32_e32 v128, v44, v44
	v_fmac_f32_e32 v129, v46, v46
	v_add_f32_e32 v128, v128, v129
	v_add_f32_e32 v2, v2, v128
	v_mul_f32_e32 v128, v41, v41
	v_mul_f32_e32 v129, v43, v43
	v_fmac_f32_e32 v128, v40, v40
	v_fmac_f32_e32 v129, v42, v42
	v_add_f32_e32 v128, v128, v129
	v_add_f32_e32 v2, v128, v2
	v_mul_f32_e32 v128, v37, v37
	v_mul_f32_e32 v129, v39, v39
	v_fmac_f32_e32 v128, v36, v36
	v_fmac_f32_e32 v129, v38, v38
	v_add_f32_e32 v128, v128, v129
	v_add_f32_e32 v2, v128, v2
	v_mov_b32_e32 v128, v2
	s_nop 1
	v_permlane16_swap_b32_e32 v128, v2
	s_waitcnt lgkmcnt(0)
	v_add_f32_e32 v2, v2, v128
	v_mov_b32_e32 v128, v2
	s_nop 1
	v_permlane32_swap_b32_e32 v128, v2
	s_and_saveexec_b64 s[0:1], s[38:39]
	s_cbranch_execz .LBB0_649
	s_lshl_b32 s6, s20, 10
	s_add_i32 s6, s10, s6
	v_lshl_add_u32 v129, v193, 4, s6
	s_waitcnt lgkmcnt(0)
	v_add_f32_e32 v2, v2, v128
	ds_write_b32 v129, v2 offset:2304
.LBB0_649:
	s_or_b64 exec, exec, s[0:1]
	v_mul_f32_e32 v2, v33, v33
	s_waitcnt lgkmcnt(0)
	v_mul_f32_e32 v128, v35, v35
	v_fmac_f32_e32 v2, v32, v32
	v_fmac_f32_e32 v128, v34, v34
	v_add_f32_e32 v2, v2, v128
	v_mul_f32_e32 v128, v29, v29
	v_mul_f32_e32 v129, v31, v31
	v_fmac_f32_e32 v128, v28, v28
	v_fmac_f32_e32 v129, v30, v30
	v_add_f32_e32 v128, v128, v129
	v_add_f32_e32 v2, v2, v128
	v_mul_f32_e32 v128, v25, v25
	v_mul_f32_e32 v129, v27, v27
	v_fmac_f32_e32 v128, v24, v24
	v_fmac_f32_e32 v129, v26, v26
	v_add_f32_e32 v128, v128, v129
	v_add_f32_e32 v2, v128, v2
	v_mul_f32_e32 v128, v21, v21
	v_mul_f32_e32 v129, v23, v23
	v_fmac_f32_e32 v128, v20, v20
	v_fmac_f32_e32 v129, v22, v22
	v_add_f32_e32 v128, v128, v129
	v_add_f32_e32 v2, v128, v2
	v_mov_b32_e32 v128, v2
	s_nop 1
	v_permlane16_swap_b32_e32 v128, v2
	s_waitcnt lgkmcnt(0)
	v_add_f32_e32 v2, v2, v128
	v_mov_b32_e32 v128, v2
	s_nop 1
	v_permlane32_swap_b32_e32 v128, v2
	s_and_saveexec_b64 s[0:1], s[38:39]
	s_cbranch_execz .LBB0_651
	s_lshl_b32 s6, s20, 10
	s_add_i32 s6, s10, s6
	v_lshl_add_u32 v129, v193, 4, s6
	s_waitcnt lgkmcnt(0)
	v_add_f32_e32 v2, v2, v128
	ds_write_b32 v129, v2 offset:2560
.LBB0_651:
	s_or_b64 exec, exec, s[0:1]
	v_mul_f32_e32 v2, v17, v17
	s_waitcnt lgkmcnt(0)
	v_mul_f32_e32 v128, v19, v19
	v_fmac_f32_e32 v2, v16, v16
	v_fmac_f32_e32 v128, v18, v18
	v_add_f32_e32 v2, v2, v128
	v_mul_f32_e32 v128, v13, v13
	v_mul_f32_e32 v129, v15, v15
	v_fmac_f32_e32 v128, v12, v12
	v_fmac_f32_e32 v129, v14, v14
	v_add_f32_e32 v128, v128, v129
	v_add_f32_e32 v2, v2, v128
	v_mul_f32_e32 v128, v9, v9
	v_mul_f32_e32 v129, v11, v11
	v_fmac_f32_e32 v128, v8, v8
	v_fmac_f32_e32 v129, v10, v10
	v_add_f32_e32 v128, v128, v129
	v_add_f32_e32 v2, v128, v2
	v_mul_f32_e32 v128, v5, v5
	v_mul_f32_e32 v129, v7, v7
	v_fmac_f32_e32 v128, v4, v4
	v_fmac_f32_e32 v129, v6, v6
	v_add_f32_e32 v128, v128, v129
	v_add_f32_e32 v2, v128, v2
	v_mov_b32_e32 v128, v2
	s_nop 1
	v_permlane16_swap_b32_e32 v128, v2
	s_waitcnt lgkmcnt(0)
	v_add_f32_e32 v2, v2, v128
	v_mov_b32_e32 v128, v2
	s_nop 1
	v_permlane32_swap_b32_e32 v128, v2
	s_and_saveexec_b64 s[0:1], s[38:39]
	s_cbranch_execz .LBB0_653
	s_lshl_b32 s6, s20, 10
	s_add_i32 s10, s10, s6
	v_lshl_add_u32 v129, v193, 4, s10
	s_waitcnt lgkmcnt(0)
	v_add_f32_e32 v2, v2, v128
	ds_write_b32 v129, v2 offset:2816
